# k3 + diff attention: meta-tile pad mask (24 v_cndmask) executed only on tile 0
# speedup vs baseline: 1.0022x; 1.0022x over previous
.LBB0_399:
	s_cmp_ge_i32 s56, s94
	s_cbranch_scc1 .LBB0_405
	ds_read_b128 v[144:147], v202 offset:0
	ds_read_b128 v[128:131], v201 offset:0
	ds_read_b128 v[148:151], v201 offset:0x2000
	ds_read_b128 v[216:219], v204 offset:0
	ds_read_b128 v[220:223], v203 offset:0
	ds_read_b128 v[224:227], v203 offset:0x2000
	s_waitcnt lgkmcnt(3)
	s_nop 0
	v_mfma_f32_32x32x16_bf16 v[128:143], v[128:131], v[144:147], 0
	v_mfma_f32_32x32x16_bf16 v[144:159], v[148:151], v[144:147], 0
	ds_read_b128 v[228:231], v207 offset:0
	ds_read_b128 v[232:235], v206 offset:0
	ds_read_b128 v[236:239], v206 offset:0x2000
	s_waitcnt lgkmcnt(3)
	v_mfma_f32_32x32x16_bf16 v[128:143], v[220:223], v[216:219], v[128:143]
	v_mfma_f32_32x32x16_bf16 v[144:159], v[224:227], v[216:219], v[144:159]
	ds_read_b128 v[216:219], v209 offset:0
	ds_read_b128 v[220:223], v208 offset:0
	ds_read_b128 v[224:227], v208 offset:0x2000
	s_waitcnt lgkmcnt(3)
	v_mfma_f32_32x32x16_bf16 v[128:143], v[232:235], v[228:231], v[128:143]
	v_mfma_f32_32x32x16_bf16 v[144:159], v[236:239], v[228:231], v[144:159]
	ds_read_b128 v[228:231], v202 offset:0x80
	ds_read_b128 v[232:235], v201 offset:0x80
	ds_read_b128 v[236:239], v201 offset:0x2080
	s_waitcnt lgkmcnt(3)
	v_mfma_f32_32x32x16_bf16 v[128:143], v[220:223], v[216:219], v[128:143]
	v_mfma_f32_32x32x16_bf16 v[144:159], v[224:227], v[216:219], v[144:159]
	ds_read_b128 v[216:219], v204 offset:0x80
	ds_read_b128 v[220:223], v203 offset:0x80
	ds_read_b128 v[224:227], v203 offset:0x2080
	s_waitcnt lgkmcnt(3)
	v_mfma_f32_32x32x16_bf16 v[128:143], v[232:235], v[228:231], v[128:143]
	v_mfma_f32_32x32x16_bf16 v[144:159], v[236:239], v[228:231], v[144:159]
	ds_read_b128 v[228:231], v207 offset:0x80
	ds_read_b128 v[232:235], v206 offset:0x80
	ds_read_b128 v[236:239], v206 offset:0x2080
	s_waitcnt lgkmcnt(3)
	v_mfma_f32_32x32x16_bf16 v[128:143], v[220:223], v[216:219], v[128:143]
	v_mfma_f32_32x32x16_bf16 v[144:159], v[224:227], v[216:219], v[144:159]
	ds_read_b128 v[216:219], v209 offset:0x80
	ds_read_b128 v[220:223], v208 offset:0x80
	ds_read_b128 v[224:227], v208 offset:0x2080
	s_waitcnt lgkmcnt(3)
	v_mfma_f32_32x32x16_bf16 v[128:143], v[232:235], v[228:231], v[128:143]
	v_mfma_f32_32x32x16_bf16 v[144:159], v[236:239], v[228:231], v[144:159]
	s_waitcnt lgkmcnt(0)
	v_mfma_f32_32x32x16_bf16 v[128:143], v[220:223], v[216:219], v[128:143]
	s_cmp_eq_u32 s56, 0
	s_cselect_b64 vcc, -1, 0
	s_mov_b32 s14, 0x41000000
	v_mfma_f32_32x32x16_bf16 v[144:159], v[224:227], v[216:219], v[144:159]
	s_cbranch_scc1 .Ldiff_pad
	s_nop 7
	v_max_f32_e32 v215, v129, v129
	v_max_f32_e32 v216, v128, v128
	v_max_f32_e32 v215, v216, v215
	v_max3_f32 v215, v215, v130, v131
	v_max3_f32 v215, v215, v132, v133
	v_max3_f32 v215, v215, v134, v135
	v_max3_f32 v215, v215, v136, v137
	v_max3_f32 v215, v215, v138, v139
	v_max3_f32 v215, v215, v140, v141
	v_max3_f32 v215, v215, v142, v143
	v_max3_f32 v215, v215, v144, v145
	v_max3_f32 v215, v215, v146, v147
	v_max3_f32 v215, v215, v148, v149
	v_max3_f32 v215, v215, v150, v151
	v_max3_f32 v215, v215, v152, v153
	v_max3_f32 v215, v215, v154, v155
	v_max3_f32 v215, v215, v156, v157
	v_max3_f32 v215, v215, v158, v159
	s_branch .Ldiff_padjoin
.Ldiff_pad:
	s_nop 7
	v_max_f32_e32 v215, v129, v129
	v_max_f32_e32 v216, v128, v128
	v_max_f32_e32 v215, v216, v215
	v_max3_f32 v215, v215, v130, v131
	v_max3_f32 v215, v215, v132, v133
	v_cndmask_b32_e32 v137, v137, v193, vcc
	v_cndmask_b32_e32 v136, v136, v193, vcc
	v_max3_f32 v215, v215, v134, v135
	v_cndmask_b32_e32 v139, v139, v193, vcc
	v_cndmask_b32_e32 v138, v138, v193, vcc
	v_max3_f32 v215, v215, v136, v137
	v_cndmask_b32_e32 v141, v141, v193, vcc
	v_cndmask_b32_e32 v140, v140, v193, vcc
	v_max3_f32 v215, v215, v138, v139
	v_cndmask_b32_e32 v143, v143, v193, vcc
	v_cndmask_b32_e32 v142, v142, v193, vcc
	v_max3_f32 v215, v215, v140, v141
	v_cndmask_b32_e32 v145, v145, v193, vcc
	v_cndmask_b32_e32 v144, v144, v193, vcc
	v_max3_f32 v215, v215, v142, v143
	v_cndmask_b32_e32 v147, v147, v193, vcc
	v_cndmask_b32_e32 v146, v146, v193, vcc
	v_max3_f32 v215, v215, v144, v145
	v_cndmask_b32_e32 v149, v149, v193, vcc
	v_cndmask_b32_e32 v148, v148, v193, vcc
	v_max3_f32 v215, v215, v146, v147
	v_cndmask_b32_e32 v151, v151, v193, vcc
	v_cndmask_b32_e32 v150, v150, v193, vcc
	v_max3_f32 v215, v215, v148, v149
	v_cndmask_b32_e32 v153, v153, v193, vcc
	v_cndmask_b32_e32 v152, v152, v193, vcc
	v_max3_f32 v215, v215, v150, v151
	v_cndmask_b32_e32 v155, v155, v193, vcc
	v_cndmask_b32_e32 v154, v154, v193, vcc
	v_max3_f32 v215, v215, v152, v153
	v_cndmask_b32_e32 v157, v157, v193, vcc
	v_cndmask_b32_e32 v156, v156, v193, vcc
	v_max3_f32 v215, v215, v154, v155
	v_cndmask_b32_e32 v159, v159, v193, vcc
	v_cndmask_b32_e32 v158, v158, v193, vcc
	v_max3_f32 v215, v215, v156, v157
	v_max3_f32 v215, v215, v158, v159
.Ldiff_padjoin:
	v_mov_b32_e32 v216, v215
	s_nop 1
	v_permlane32_swap_b32_e32 v215, v216
	v_max_f32_e32 v216, v216, v216
	v_max_f32_e32 v215, v215, v215
	v_max_f32_e32 v215, v215, v216
	v_sub_f32_e32 v216, v215, v210
	v_mul_f32_e32 v216, 0x3db504f3, v216
	v_cmp_ge_f32_e32 vcc, s14, v216
	v_max_f32_e32 v217, v210, v210
	s_cmp_eq_u64 vcc, exec
	v_max_f32_e32 v217, v217, v215
	s_cselect_b64 vcc, -1, 0
	v_sub_f32_e32 v215, v210, v217
	v_cndmask_b32_e32 v210, v217, v210, vcc
	v_mul_f32_e32 v216, 0xbe0293ee, v210
	v_fmamk_f32 v128, v128, 0x3e0293ee, v216
	v_fmamk_f32 v129, v129, 0x3e0293ee, v216
	v_exp_f32_e32 v128, v128
	v_fmamk_f32 v130, v130, 0x3e0293ee, v216
	v_exp_f32_e32 v129, v129
	v_fmamk_f32 v131, v131, 0x3e0293ee, v216
	v_exp_f32_e32 v130, v130
	v_fmamk_f32 v132, v132, 0x3e0293ee, v216
	v_fmamk_f32 v133, v133, 0x3e0293ee, v216
	v_fmamk_f32 v134, v134, 0x3e0293ee, v216
	v_fmamk_f32 v135, v135, 0x3e0293ee, v216
	v_fmamk_f32 v136, v136, 0x3e0293ee, v216
	v_fmamk_f32 v137, v137, 0x3e0293ee, v216
	v_fmamk_f32 v138, v138, 0x3e0293ee, v216
	v_fmamk_f32 v139, v139, 0x3e0293ee, v216
	v_fmamk_f32 v140, v140, 0x3e0293ee, v216
	v_fmamk_f32 v141, v141, 0x3e0293ee, v216
	v_fmamk_f32 v142, v142, 0x3e0293ee, v216
	v_fmamk_f32 v143, v143, 0x3e0293ee, v216
	v_fmamk_f32 v144, v144, 0x3e0293ee, v216
	v_fmamk_f32 v145, v145, 0x3e0293ee, v216
	v_fmamk_f32 v146, v146, 0x3e0293ee, v216
	v_fmamk_f32 v147, v147, 0x3e0293ee, v216
	v_fmamk_f32 v148, v148, 0x3e0293ee, v216
	v_fmamk_f32 v149, v149, 0x3e0293ee, v216
	v_fmamk_f32 v150, v150, 0x3e0293ee, v216
	v_fmamk_f32 v151, v151, 0x3e0293ee, v216
	v_fmamk_f32 v152, v152, 0x3e0293ee, v216
	v_fmamk_f32 v153, v153, 0x3e0293ee, v216
	v_fmamk_f32 v154, v154, 0x3e0293ee, v216
	v_fmamk_f32 v155, v155, 0x3e0293ee, v216
	v_fmamk_f32 v156, v156, 0x3e0293ee, v216
	v_fmamk_f32 v157, v157, 0x3e0293ee, v216
	v_fmamk_f32 v158, v158, 0x3e0293ee, v216
	v_fmac_f32_e32 v216, 0x3e0293ee, v159
	v_exp_f32_e32 v131, v131
	v_exp_f32_e32 v132, v132
	v_exp_f32_e32 v159, v216
	v_add_f32_e32 v216, 0, v128
	v_exp_f32_e32 v133, v133
	v_add_f32_e32 v216, v129, v216
	v_exp_f32_e32 v134, v134
	v_add_f32_e32 v216, v130, v216
	v_exp_f32_e32 v135, v135
	v_add_f32_e32 v216, v131, v216
	v_exp_f32_e32 v136, v136
	v_add_f32_e32 v216, v132, v216
	v_exp_f32_e32 v137, v137
	v_add_f32_e32 v216, v133, v216
	v_exp_f32_e32 v138, v138
	v_add_f32_e32 v216, v134, v216
	v_exp_f32_e32 v139, v139
	v_add_f32_e32 v216, v135, v216
	v_exp_f32_e32 v140, v140
	v_add_f32_e32 v216, v136, v216
	v_exp_f32_e32 v141, v141
	v_add_f32_e32 v216, v137, v216
	v_exp_f32_e32 v142, v142
	v_add_f32_e32 v216, v138, v216
	v_exp_f32_e32 v143, v143
	v_add_f32_e32 v216, v139, v216
	v_exp_f32_e32 v144, v144
	v_add_f32_e32 v216, v140, v216
	v_exp_f32_e32 v145, v145
	v_add_f32_e32 v216, v141, v216
	v_exp_f32_e32 v146, v146
	v_add_f32_e32 v216, v142, v216
	v_exp_f32_e32 v147, v147
	v_add_f32_e32 v216, v143, v216
	v_exp_f32_e32 v148, v148
	v_add_f32_e32 v216, v144, v216
	v_exp_f32_e32 v149, v149
	v_add_f32_e32 v216, v145, v216
	v_exp_f32_e32 v150, v150
	v_add_f32_e32 v216, v146, v216
	v_exp_f32_e32 v151, v151
	v_add_f32_e32 v216, v147, v216
	v_exp_f32_e32 v152, v152
	v_add_f32_e32 v216, v148, v216
	v_exp_f32_e32 v153, v153
	v_add_f32_e32 v216, v149, v216
	v_exp_f32_e32 v154, v154
	v_add_f32_e32 v216, v150, v216
	v_exp_f32_e32 v155, v155
	v_add_f32_e32 v216, v151, v216
	v_exp_f32_e32 v156, v156
	v_add_f32_e32 v216, v152, v216
	v_exp_f32_e32 v157, v157
	v_add_f32_e32 v216, v153, v216
	v_exp_f32_e32 v158, v158
	v_add_f32_e32 v216, v154, v216
	v_mul_f32_e32 v215, 0x3e0293ee, v215
	v_add_f32_e32 v216, v155, v216
	v_exp_f32_e32 v215, v215
	v_add_f32_e32 v216, v156, v216
	v_add_f32_e32 v216, v157, v216
	v_add_f32_e32 v216, v158, v216
	v_add_f32_e32 v216, v159, v216
	v_cndmask_b32_e64 v215, v215, 1.0, vcc
	v_mov_b32_e32 v217, v216
	v_cvt_pk_bf16_f32 v128, v128, v129
	v_cvt_pk_bf16_f32 v129, v130, v131
	v_cvt_pk_bf16_f32 v130, v132, v133
	v_cvt_pk_bf16_f32 v131, v134, v135
	v_cvt_pk_bf16_f32 v132, v136, v137
	v_cvt_pk_bf16_f32 v133, v138, v139
	v_cvt_pk_bf16_f32 v134, v140, v141
	v_cvt_pk_bf16_f32 v135, v142, v143
	v_cvt_pk_bf16_f32 v136, v144, v145
	v_cvt_pk_bf16_f32 v137, v146, v147
	v_cvt_pk_bf16_f32 v138, v148, v149
	v_cvt_pk_bf16_f32 v139, v150, v151
	v_cvt_pk_bf16_f32 v140, v152, v153
	v_cvt_pk_bf16_f32 v141, v154, v155
	v_cvt_pk_bf16_f32 v142, v156, v157
	v_cvt_pk_bf16_f32 v143, v158, v159
	s_nop 1
	v_permlane32_swap_b32_e32 v216, v217
	v_permlane32_swap_b32_e32 v128, v130
	v_permlane32_swap_b32_e32 v129, v131
	v_permlane32_swap_b32_e32 v132, v134
	v_permlane32_swap_b32_e32 v133, v135
	v_permlane32_swap_b32_e32 v136, v138
	v_permlane32_swap_b32_e32 v137, v139
	v_permlane32_swap_b32_e32 v140, v142
	v_permlane32_swap_b32_e32 v141, v143
	v_cmp_gt_f32_e32 vcc, 1.0, v215
	s_cbranch_vccz .LBB0_404
	s_and_saveexec_b64 s[56:57], s[4:5]
	ds_write_b32 v205, v215 offset:128
	s_or_b64 exec, exec, s[56:57]
	s_waitcnt lgkmcnt(0)
	v_add_u32_e32 v144, s63, v184
	ds_read_b128 v[156:159], v144 offset:224
	ds_read_b128 v[152:155], v144 offset:192
	ds_read_b128 v[148:151], v144 offset:160
	ds_read_b128 v[144:147], v144 offset:128
	s_waitcnt lgkmcnt(3)
	v_pk_mul_f32 v[76:77], v[76:77], v[156:157]
	s_waitcnt lgkmcnt(2)
	v_pk_mul_f32 v[72:73], v[72:73], v[152:153]
	s_waitcnt lgkmcnt(1)
	v_pk_mul_f32 v[68:69], v[68:69], v[148:149]
	v_pk_mul_f32 v[78:79], v[78:79], v[158:159]
	v_pk_mul_f32 v[74:75], v[74:75], v[154:155]
	v_pk_mul_f32 v[70:71], v[70:71], v[150:151]
	s_waitcnt lgkmcnt(0)
	v_pk_mul_f32 v[66:67], v[66:67], v[146:147]
	v_pk_mul_f32 v[64:65], v[64:65], v[144:145]
	v_pk_mul_f32 v[124:125], v[124:125], v[156:157]
	v_pk_mul_f32 v[120:121], v[120:121], v[152:153]
	v_pk_mul_f32 v[116:117], v[116:117], v[148:149]
	v_pk_mul_f32 v[126:127], v[126:127], v[158:159]
	v_pk_mul_f32 v[122:123], v[122:123], v[154:155]
	v_pk_mul_f32 v[118:119], v[118:119], v[150:151]
	v_pk_mul_f32 v[114:115], v[114:115], v[146:147]
	v_pk_mul_f32 v[112:113], v[112:113], v[144:145]
	v_pk_mul_f32 v[108:109], v[108:109], v[156:157]
	v_pk_mul_f32 v[104:105], v[104:105], v[152:153]
	v_pk_mul_f32 v[100:101], v[100:101], v[148:149]
	v_pk_mul_f32 v[110:111], v[110:111], v[158:159]
	v_pk_mul_f32 v[106:107], v[106:107], v[154:155]
	v_pk_mul_f32 v[102:103], v[102:103], v[150:151]
	v_pk_mul_f32 v[98:99], v[98:99], v[146:147]
	v_pk_mul_f32 v[96:97], v[96:97], v[144:145]
	v_pk_mul_f32 v[92:93], v[92:93], v[156:157]
	v_pk_mul_f32 v[88:89], v[88:89], v[152:153]
	v_pk_mul_f32 v[84:85], v[84:85], v[148:149]
	v_pk_mul_f32 v[94:95], v[94:95], v[158:159]
	v_pk_mul_f32 v[90:91], v[90:91], v[154:155]
	v_pk_mul_f32 v[86:87], v[86:87], v[150:151]
	v_pk_mul_f32 v[82:83], v[82:83], v[146:147]
	v_pk_mul_f32 v[80:81], v[80:81], v[144:145]
	v_pk_mul_f32 v[60:61], v[60:61], v[156:157]
	v_pk_mul_f32 v[56:57], v[56:57], v[152:153]
	v_pk_mul_f32 v[52:53], v[52:53], v[148:149]
	v_pk_mul_f32 v[62:63], v[62:63], v[158:159]
	v_pk_mul_f32 v[58:59], v[58:59], v[154:155]
	v_pk_mul_f32 v[54:55], v[54:55], v[150:151]
	v_pk_mul_f32 v[50:51], v[50:51], v[146:147]
	v_pk_mul_f32 v[48:49], v[48:49], v[144:145]
	v_pk_mul_f32 v[44:45], v[44:45], v[156:157]
	v_pk_mul_f32 v[40:41], v[40:41], v[152:153]
	v_pk_mul_f32 v[36:37], v[36:37], v[148:149]
	v_pk_mul_f32 v[46:47], v[46:47], v[158:159]
	v_pk_mul_f32 v[42:43], v[42:43], v[154:155]
	v_pk_mul_f32 v[38:39], v[38:39], v[150:151]
	v_pk_mul_f32 v[34:35], v[34:35], v[146:147]
	v_pk_mul_f32 v[32:33], v[32:33], v[144:145]
	v_pk_mul_f32 v[28:29], v[28:29], v[156:157]
	v_pk_mul_f32 v[24:25], v[24:25], v[152:153]
	v_pk_mul_f32 v[20:21], v[20:21], v[148:149]
	v_pk_mul_f32 v[30:31], v[30:31], v[158:159]
	v_pk_mul_f32 v[26:27], v[26:27], v[154:155]
	v_pk_mul_f32 v[22:23], v[22:23], v[150:151]
	v_pk_mul_f32 v[18:19], v[18:19], v[146:147]
	v_pk_mul_f32 v[16:17], v[16:17], v[144:145]
	v_pk_mul_f32 v[12:13], v[12:13], v[156:157]
	v_pk_mul_f32 v[8:9], v[8:9], v[152:153]
	v_pk_mul_f32 v[4:5], v[4:5], v[148:149]
	v_pk_mul_f32 v[14:15], v[14:15], v[158:159]
	v_pk_mul_f32 v[10:11], v[10:11], v[154:155]
	v_pk_mul_f32 v[6:7], v[6:7], v[150:151]
	v_pk_mul_f32 v[2:3], v[2:3], v[146:147]
	v_pk_mul_f32 v[0:1], v[0:1], v[144:145]
